# cross attention: K and V tiles fetched once per workgroup into shared LDS tiles (2 global loads + 2 LDS writes per wave and key step instead of 16 + 8); per-wave V staging and its address code removed
# speedup vs baseline: 1.0144x; 1.0062x over previous
; __device__ __forceinline__ void xattn_mfma_item(const bf16* qx, const bf16* kv, bf16* ox, LAS unsigned char* wl, int item, int lane) {
;     ...
;     const int trbase = (4 * hi + ((lane >> 2) & 3)) * PV128 + (16 * ((lane >> 4) & 1) + 4 * (lane & 3)) * 2;
;     const char* kvc = (const char*)(kv + (size_t)b * MEML * 1024);
;     const unsigned kfo = (unsigned)(r * 1024 + head * 128 + 8 * hi) * 2u;
;     const unsigned vlo = (unsigned)((lane >> 4) * 1024 + 512 + head * 128 + 8 * (lane & 15)) * 2u;
.LBB0_584:
	s_and_b64 vcc, exec, s[18:19]
	s_cbranch_vccz .LBB0_620
	s_add_u32 s2, s80, 0xac00000
	s_addc_u32 s3, s81, 0
	v_writelane_b32 v253, s2, 47
	v_and_b32_e32 v202, 63, v1
	s_nop 0
	v_writelane_b32 v253, s3, 48
	s_add_u32 s2, s80, 0xf000000
	s_addc_u32 s3, s81, 0
	v_writelane_b32 v253, s2, 49
	s_nop 1
	v_writelane_b32 v253, s3, 50
	s_ashr_i32 s2, s41, 6
	v_writelane_b32 v253, s2, 51
	s_cmp_gt_i32 s38, 1
	s_cbranch_scc0 .LBB0_596
	s_cmp_gt_i32 s38, 3
	s_mov_b64 s[2:3], -1
	s_cbranch_scc0 .LBB0_614
	v_readlane_b32 s2, v253, 10
	v_readlane_b32 s3, v253, 51
	s_add_i32 s10, s3, s2
	s_cmpk_gt_i32 s10, 0x7ff
	s_cbranch_scc1 .LBB0_613
	s_lshr_b32 s2, s10, 5
	s_lshl_b32 s2, s2, 3
	s_and_b32 s3, s10, 7
	s_add_i32 s2, s2, s3
	s_lshl_b32 s2, s2, 2
	s_bfe_u32 s3, s10, 0x20003
	s_or_b32 s10, s2, s3
	s_lshl_b64 s[2:3], s[78:79], 19
	s_and_b32 s2, s2, 0xffc00000
	s_lshl_b64 s[14:15], s[0:1], 22
	v_readlane_b32 s16, v253, 49
	v_readlane_b32 s17, v253, 50
	s_add_u32 s1, s16, s14
	s_addc_u32 s11, s17, s15
	v_readlane_b32 s15, v253, 51
	s_lshl_b32 s14, s15, 14
	s_add_i32 s14, s14, 0
	v_and_b32_e32 v5, 16, v1
	v_lshlrev_b32_e32 v6, 2, v202
	v_lshrrev_b32_e32 v2, 5, v202
	v_and_or_b32 v5, v6, 12, v5
	v_and_b32_e32 v6, 15, v1
	s_add_u32 s2, s12, s2
	v_lshlrev_b32_e32 v219, 3, v2
	v_lshlrev_b32_e32 v220, 2, v2
	v_lshrrev_b32_e32 v2, 2, v1
	v_lshrrev_b32_e32 v4, 4, v202
	v_lshlrev_b32_e32 v7, 3, v6
	s_addc_u32 s3, s13, s3
	v_and_or_b32 v2, v2, 3, v220
	v_lshl_or_b32 v222, v4, 10, v7
	v_mov_b32_e32 v7, s14
	s_movk_i32 s14, 0x110
	s_add_u32 s12, s62, s2
	v_mad_u32_u24 v4, v4, s14, v7
	v_mad_u32_u24 v2, v2, s14, v7
	s_addc_u32 s13, s63, s3
	s_lshl_b32 s14, s15, 7
	v_readlane_b32 s15, v253, 36
	s_lshl_b32 s14, s10, 7
	v_readlane_b32 s15, v253, 38
	v_and_b32_e32 v203, 31, v1
	v_lshlrev_b32_e32 v5, 1, v5
	v_lshlrev_b32_e32 v6, 4, v6
	s_add_u32 s15, s15, s2
	v_readlane_b32 s2, v253, 39
	v_lshl_or_b32 v221, v203, 10, v219
	s_addc_u32 s16, s2, s3
	v_add_u32_e32 v223, v4, v6
	v_add_u32_e32 v224, v2, v5
	v_readlane_b32 s21, v253, 51
	s_nop 3
	s_lshl_b32 s21, s21, 14
	v_subrev_u32_e32 v224, s21, v224
	s_branch .LBB0_590

; __device__ __forceinline__ void xattn_mfma_item(const bf16* qx, const bf16* kv, bf16* ox, LAS unsigned char* wl, int item, int lane) {
;     ...
;     { const char* qb_ = (const char*)qx; const unsigned qo = (unsigned)(token * DX + head * 128 + 8 * hi) * 2u;
; #pragma unroll
;       for (int d0 = 0; d0 < 8; ++d0) Qf[d0] = *(const s16x8*)(qb_ + qo + 32 * d0); }
;     f32x16 O[4];
; #pragma unroll
;     for (int k = 0; k < 4; ++k)
; #pragma unroll
;         for (int i = 0; i < 16; ++i) O[k][i] = 0.f;
;     float mrun = -1e30f, lsum = 0.f;
;     const int trbase = (4 * hi + ((lane >> 2) & 3)) * PV128 + (16 * ((lane >> 4) & 1) + 4 * (lane & 3)) * 2;
;     const char* kvc = (const char*)(kv + (size_t)b * MEML * 1024);
;     const unsigned kfo = (unsigned)(r * 1024 + head * 128 + 8 * hi) * 2u;
;     const unsigned vlo = (unsigned)((lane >> 4) * 1024 + 512 + head * 128 + 8 * (lane & 15)) * 2u;
;     s16x8 Kn[8]; v4u vn[8];
; #pragma unroll
;     for (int d0 = 0; d0 < 8; ++d0) Kn[d0] = *(const s16x8*)(kvc + kfo + 32 * d0);
; #pragma unroll
;     for (int i = 0; i < 8; ++i) vn[i] = *(const v4u*)(kvc + vlo + (size_t)(4 * i) * 2048);
.LBB0_590:
	s_and_b32 s2, s14, 0x180
	s_lshl_b32 s3, s10, 7
	v_add_lshl_u32 v2, v222, s2, 1
	v_add_lshl_u32 v4, v221, s2, 1
	s_lshl_b32 s2, s10, 3
	s_and_b32 s17, s3, 0x180
	s_bfe_i32 s3, s10, 0x1001c
	s_andn2_b32 s2, s2, 31
	s_lshr_b32 s3, s3, 21
	v_or_b32_e32 v6, s2, v203
	s_add_i32 s2, s2, s3
	v_lshl_or_b32 v225, v6, 9, s17
	s_ashr_i32 s2, s2, 11
	v_or_b32_e32 v6, v225, v219
	v_readlane_b32 s18, v253, 47
	s_ashr_i32 s3, s2, 31
	v_lshlrev_b32_e32 v6, 1, v6
	v_readlane_b32 s19, v253, 48
	s_lshl_b64 s[2:3], s[2:3], 19
	s_nop 3
	global_load_dwordx4 v[130:133], v6, s[18:19]
	global_load_dwordx4 v[126:129], v6, s[18:19] offset:32
	global_load_dwordx4 v[122:125], v6, s[18:19] offset:64
	global_load_dwordx4 v[118:121], v6, s[18:19] offset:96
	global_load_dwordx4 v[114:117], v6, s[18:19] offset:128
	global_load_dwordx4 v[110:113], v6, s[18:19] offset:160
	global_load_dwordx4 v[102:105], v6, s[18:19] offset:192
	global_load_dwordx4 v[98:101], v6, s[18:19] offset:224
	s_add_u32 s18, s1, s2
	v_or_b32_e32 v6, s17, v221
	s_addc_u32 s19, s11, s3
	v_lshlrev_b32_e32 v7, 1, v6
	v_or_b32_e32 v6, s17, v222
	v_lshlrev_b32_e32 v6, 1, v6
	v_readlane_b32 s21, v253, 51
	v_lshrrev_b32_e32 v234, 4, v202
	v_and_b32_e32 v235, 15, v202
	v_lshrrev_b32_e32 v238, 5, v202
	v_lshl_add_u32 v234, s21, 2, v234
	v_lshlrev_b32_e32 v235, 4, v235
	v_lshl_add_u32 v236, v234, 11, v235
	v_lshl_add_u32 v236, s17, 1, v236
	v_mov_b32_e32 v237, 0
	v_lshl_add_u64 v[232:233], s[18:19], 0, v[236:237]
	global_load_dwordx4 v[228:231], v[232:233], off
	global_load_dwordx4 v[240:243], v[232:233], off offset:1024
	v_mul_u32_u24_e32 v234, 0x110, v234
	v_add_u32_e32 v234, v234, v235
	v_mov_b32_e32 v239, v234
	v_add_u32_e32 v234, 0x20000, v234
	v_mul_u32_u24_e32 v235, 0x110, v203
	v_lshl_add_u32 v235, v238, 4, v235
	v_add_u32_e32 v235, 0x20000, v235
	v_mov_b32_e32 v7, v3
	v_lshl_add_u64 v[8:9], s[18:19], 0, v[6:7]
	v_add_co_u32_e32 v6, vcc, s83, v8
	s_movk_i32 s17, 0x6000
	s_nop 0
	v_addc_co_u32_e32 v7, vcc, 0, v9, vcc
	v_add_co_u32_e32 v6, vcc, s88, v8
	s_add_u32 s18, s12, s2
	s_nop 0
	v_addc_co_u32_e32 v7, vcc, 0, v9, vcc
	v_add_co_u32_e32 v6, vcc, s17, v8
	s_mov_b32 s17, 0x8000
	s_nop 0
	v_addc_co_u32_e32 v7, vcc, 0, v9, vcc
	v_add_co_u32_e32 v6, vcc, s17, v8
	s_mov_b32 s17, 0xa000
	s_nop 0
	v_addc_co_u32_e32 v7, vcc, 0, v9, vcc
	v_add_co_u32_e32 v6, vcc, s17, v8
	s_mov_b32 s17, 0xc000
	s_nop 0
	v_addc_co_u32_e32 v7, vcc, 0, v9, vcc
	v_add_co_u32_e32 v6, vcc, s17, v8
	s_mov_b32 s17, 0xe000
	s_nop 0
	v_addc_co_u32_e32 v7, vcc, 0, v9, vcc
	v_add_co_u32_e32 v6, vcc, s17, v8
	s_addc_u32 s19, s13, s3
	s_nop 0
	v_addc_co_u32_e32 v7, vcc, 0, v9, vcc
	s_add_u32 s2, s15, s2
	v_mov_b32_e32 v5, v3
	s_addc_u32 s3, s16, s3
	v_mov_b32_e32 v16, v3
	v_mov_b32_e32 v17, v3
	v_lshl_add_u64 v[204:205], s[18:19], 0, v[2:3]
	v_lshl_add_u64 v[206:207], s[2:3], 0, v[4:5]
	v_mov_b32_e32 v2, v3
	v_mov_b32_e32 v4, v3
	v_mov_b32_e32 v6, v3
	v_mov_b32_e32 v7, v3
	v_mov_b32_e32 v8, v3
	v_mov_b32_e32 v9, v3
	v_mov_b32_e32 v10, v3
	v_mov_b32_e32 v11, v3
	v_mov_b32_e32 v12, v3
	v_mov_b32_e32 v13, v3
	v_mov_b32_e32 v14, v3
	v_mov_b32_e32 v15, v3
	v_mov_b64_e32 v[32:33], v[16:17]
	v_mov_b64_e32 v[48:49], v[16:17]
	v_mov_b64_e32 v[64:65], v[16:17]
	v_mov_b64_e32 v[80:81], v[16:17]
	v_mov_b32_e32 v226, 0
	v_mov_b32_e32 v227, 0xf149f2ca
	s_mov_b64 s[2:3], 0
	v_mov_b64_e32 v[30:31], v[14:15]
	v_mov_b64_e32 v[28:29], v[12:13]
	v_mov_b64_e32 v[26:27], v[10:11]
	v_mov_b64_e32 v[24:25], v[8:9]
	v_mov_b64_e32 v[22:23], v[6:7]
	v_mov_b64_e32 v[20:21], v[4:5]
	v_mov_b64_e32 v[18:19], v[2:3]
	v_mov_b64_e32 v[46:47], v[14:15]
	v_mov_b64_e32 v[44:45], v[12:13]
	v_mov_b64_e32 v[42:43], v[10:11]
	v_mov_b64_e32 v[40:41], v[8:9]
	v_mov_b64_e32 v[38:39], v[6:7]
	v_mov_b64_e32 v[36:37], v[4:5]
	v_mov_b64_e32 v[34:35], v[2:3]
	v_mov_b64_e32 v[62:63], v[14:15]
	v_mov_b64_e32 v[60:61], v[12:13]
	v_mov_b64_e32 v[58:59], v[10:11]
	v_mov_b64_e32 v[56:57], v[8:9]
	v_mov_b64_e32 v[54:55], v[6:7]
	v_mov_b64_e32 v[52:53], v[4:5]
	v_mov_b64_e32 v[50:51], v[2:3]
	v_mov_b64_e32 v[78:79], v[14:15]
	v_mov_b64_e32 v[76:77], v[12:13]
	v_mov_b64_e32 v[74:75], v[10:11]
	v_mov_b64_e32 v[72:73], v[8:9]
	v_mov_b64_e32 v[70:71], v[6:7]
	v_mov_b64_e32 v[68:69], v[4:5]
	v_mov_b64_e32 v[66:67], v[2:3]
	s_waitcnt vmcnt(1)
	ds_write_b128 v234, v[228:231]
	s_waitcnt lgkmcnt(0)
	s_barrier
	ds_read_b128 v[158:161], v235
	ds_read_b128 v[154:157], v235 offset:32
	ds_read_b128 v[150:153], v235 offset:64
	ds_read_b128 v[146:149], v235 offset:96
	ds_read_b128 v[142:145], v235 offset:128
	ds_read_b128 v[138:141], v235 offset:160
	ds_read_b128 v[134:137], v235 offset:192
	ds_read_b128 v[106:109], v235 offset:224
	v_add_co_u32_e32 v232, vcc, 0x10000, v232
	s_nop 1
	v_addc_co_u32_e32 v233, vcc, 0, v233, vcc
	global_load_dwordx4 v[228:231], v[232:233], off
	s_branch .LBB0_592

; #define LAS __attribute__((address_space(3)))
; #define MFMA32(a, b, c) __builtin_amdgcn_mfma_f32_32x32x16_bf16(a, b, c, 0, 0, 0)
; __device__ __forceinline__ float xh_max(float x) { auto rr = __builtin_amdgcn_permlane32_swap(__float_as_uint(x), __float_as_uint(x), false, false); return fmaxf(__uint_as_float(rr[0]), __uint_as_float(rr[1])); }
; __device__ __forceinline__ void xattn_mfma_item(const bf16* qx, const bf16* kv, bf16* ox, LAS unsigned char* wl, int item, int lane) {
;     ...
; #pragma unroll
;         for (int d0 = 0; d0 < 8; ++d0) Sx = MFMA32(Kn[d0], Qf[d0], Sx);
;         { LAS unsigned char* dst = wl + (lane >> 4) * PV128 + 16 * (lane & 15);
; #pragma unroll
;           for (int i = 0; i < 8; ++i) *(LAS v4u*)(dst + 4 * i * PV128) = vn[i]; }
;         if (jt < 7) { const char* tb = kvc + (size_t)((jt + 1) * 32) * 2048;
; #pragma unroll
;             for (int d0 = 0; d0 < 8; ++d0) Kn[d0] = *(const s16x8*)(tb + kfo + 32 * d0);
; #pragma unroll
;             for (int i = 0; i < 8; ++i) vn[i] = *(const v4u*)(tb + vlo + (size_t)(4 * i) * 2048); }
;         float P[16]; float tmax = -1e30f;
; #pragma unroll
;         for (int i = 0; i < 16; ++i) { P[i] = Sx[i] * SCX; tmax = fmaxf(tmax, P[i]); }
;         tmax = xh_max(tmax);
;         if (__any(tmax > mrun)) { const float mnew = fmaxf(mrun, tmax), alpha = __builtin_amdgcn_exp2f(mrun - mnew); lsum *= alpha; mrun = mnew;
.LBB0_592:
	s_waitcnt lgkmcnt(0)
	v_mfma_f32_32x32x16_bf16 v[82:97], v[158:161], v[130:133], 0
	v_mfma_f32_32x32x16_bf16 v[82:97], v[154:157], v[126:129], v[82:97]
	v_mfma_f32_32x32x16_bf16 v[82:97], v[150:153], v[122:125], v[82:97]
	v_mfma_f32_32x32x16_bf16 v[82:97], v[146:149], v[118:121], v[82:97]
	v_mfma_f32_32x32x16_bf16 v[82:97], v[142:145], v[114:117], v[82:97]
	v_mfma_f32_32x32x16_bf16 v[82:97], v[138:141], v[110:113], v[82:97]
	v_mfma_f32_32x32x16_bf16 v[82:97], v[134:137], v[102:105], v[82:97]
	v_mfma_f32_32x32x16_bf16 v[82:97], v[106:109], v[98:101], v[82:97]
	s_barrier
	s_waitcnt vmcnt(0)
	ds_write_b128 v234, v[228:231]
	ds_write_b128 v239, v[240:243]
	s_waitcnt lgkmcnt(0)
	s_barrier
	ds_read_b128 v[158:161], v235
	ds_read_b128 v[154:157], v235 offset:32
	ds_read_b128 v[150:153], v235 offset:64
	ds_read_b128 v[146:149], v235 offset:96
	ds_read_b128 v[142:145], v235 offset:128
	ds_read_b128 v[138:141], v235 offset:160
	ds_read_b128 v[134:137], v235 offset:192
	ds_read_b128 v[106:109], v235 offset:224
	global_load_dwordx4 v[240:243], v[232:233], off offset:1024
	s_cmp_gt_u32 s2, 0x50000
	s_cbranch_scc1 .Lxa_nopiece
	v_add_co_u32_e32 v232, vcc, 0x10000, v232
	s_nop 1
	v_addc_co_u32_e32 v233, vcc, 0, v233, vcc
	global_load_dwordx4 v[228:231], v[232:233], off
.Lxa_nopiece:
	v_mul_f32_e32 v82, 0x3e0293ee, v82
	v_mul_f32_e32 v17, 0x3e0293ee, v83
	s_mov_b32 s17, 0xf149f2ca
	v_max3_f32 v2, v82, s17, v17
	v_mul_f32_e32 v16, 0x3e0293ee, v84
	v_mul_f32_e32 v15, 0x3e0293ee, v85
	v_max3_f32 v2, v2, v16, v15
	v_mul_f32_e32 v14, 0x3e0293ee, v86
	v_mul_f32_e32 v13, 0x3e0293ee, v87
	v_max3_f32 v2, v2, v14, v13
	v_mul_f32_e32 v12, 0x3e0293ee, v88
	v_mul_f32_e32 v11, 0x3e0293ee, v89
	v_max3_f32 v2, v2, v12, v11
	v_mul_f32_e32 v10, 0x3e0293ee, v90
	v_mul_f32_e32 v9, 0x3e0293ee, v91
	v_max3_f32 v2, v2, v10, v9
	v_mul_f32_e32 v8, 0x3e0293ee, v92
	v_mul_f32_e32 v7, 0x3e0293ee, v93
	v_max3_f32 v2, v2, v8, v7
	v_mul_f32_e32 v6, 0x3e0293ee, v94
	v_mul_f32_e32 v5, 0x3e0293ee, v95
	v_max3_f32 v83, v2, v6, v5
	v_mul_f32_e32 v4, 0x3e0293ee, v96
	v_mul_f32_e32 v2, 0x3e0293ee, v97
	v_max3_f32 v83, v83, v4, v2
	v_mov_b32_e32 v84, v83
	s_nop 1
	v_permlane32_swap_b32_e32 v83, v84
	v_max_f32_e32 v84, v84, v84
	v_max_f32_e32 v83, v83, v83
	v_max_f32_e32 v83, v83, v84
	v_cmp_gt_f32_e32 vcc, v83, v227
	s_cbranch_vccz .LBB0_591
	v_max_f32_e32 v83, v83, v83
	v_max_f32_e32 v84, v227, v227
	v_max_f32_e32 v83, v84, v83
	v_sub_f32_e32 v84, v227, v83
	v_exp_f32_e32 v84, v84
	v_mov_b32_e32 v227, v83
	v_pk_mul_f32 v[80:81], v[80:81], v[84:85] op_sel_hi:[1,0]
	v_pk_mul_f32 v[78:79], v[78:79], v[84:85] op_sel_hi:[1,0]
	v_pk_mul_f32 v[76:77], v[76:77], v[84:85] op_sel_hi:[1,0]
	v_pk_mul_f32 v[74:75], v[74:75], v[84:85] op_sel_hi:[1,0]
	v_pk_mul_f32 v[72:73], v[72:73], v[84:85] op_sel_hi:[1,0]
	v_pk_mul_f32 v[70:71], v[70:71], v[84:85] op_sel_hi:[1,0]
	v_pk_mul_f32 v[68:69], v[68:69], v[84:85] op_sel_hi:[1,0]
	v_pk_mul_f32 v[66:67], v[66:67], v[84:85] op_sel_hi:[1,0]
	v_pk_mul_f32 v[64:65], v[64:65], v[84:85] op_sel_hi:[1,0]
	v_pk_mul_f32 v[62:63], v[62:63], v[84:85] op_sel_hi:[1,0]
	v_pk_mul_f32 v[60:61], v[60:61], v[84:85] op_sel_hi:[1,0]
	v_pk_mul_f32 v[58:59], v[58:59], v[84:85] op_sel_hi:[1,0]
	v_pk_mul_f32 v[56:57], v[56:57], v[84:85] op_sel_hi:[1,0]
	v_pk_mul_f32 v[54:55], v[54:55], v[84:85] op_sel_hi:[1,0]
	v_pk_mul_f32 v[52:53], v[52:53], v[84:85] op_sel_hi:[1,0]
	v_pk_mul_f32 v[50:51], v[50:51], v[84:85] op_sel_hi:[1,0]
	v_pk_mul_f32 v[48:49], v[48:49], v[84:85] op_sel_hi:[1,0]
	v_pk_mul_f32 v[46:47], v[46:47], v[84:85] op_sel_hi:[1,0]
	v_pk_mul_f32 v[44:45], v[44:45], v[84:85] op_sel_hi:[1,0]
	v_pk_mul_f32 v[42:43], v[42:43], v[84:85] op_sel_hi:[1,0]
	v_pk_mul_f32 v[40:41], v[40:41], v[84:85] op_sel_hi:[1,0]
	v_pk_mul_f32 v[38:39], v[38:39], v[84:85] op_sel_hi:[1,0]
	v_pk_mul_f32 v[36:37], v[36:37], v[84:85] op_sel_hi:[1,0]
	v_pk_mul_f32 v[34:35], v[34:35], v[84:85] op_sel_hi:[1,0]
	v_pk_mul_f32 v[32:33], v[32:33], v[84:85] op_sel_hi:[1,0]
	v_pk_mul_f32 v[30:31], v[30:31], v[84:85] op_sel_hi:[1,0]
	v_pk_mul_f32 v[28:29], v[28:29], v[84:85] op_sel_hi:[1,0]
	v_pk_mul_f32 v[26:27], v[26:27], v[84:85] op_sel_hi:[1,0]
	v_pk_mul_f32 v[24:25], v[24:25], v[84:85] op_sel_hi:[1,0]
	v_pk_mul_f32 v[22:23], v[22:23], v[84:85] op_sel_hi:[1,0]
	v_pk_mul_f32 v[20:21], v[20:21], v[84:85] op_sel_hi:[1,0]
	v_pk_mul_f32 v[18:19], v[18:19], v[84:85] op_sel_hi:[1,0]
	v_mul_f32_e32 v226, v226, v84
	s_branch .LBB0_591
; #define LAS __attribute__((address_space(3)))
; #define MFMA32(a, b, c) __builtin_amdgcn_mfma_f32_32x32x16_bf16(a, b, c, 0, 0, 0)
; __device__ __forceinline__ float xh_max(float x) { auto rr = __builtin_amdgcn_permlane32_swap(__float_as_uint(x), __float_as_uint(x), false, false); return fmaxf(__uint_as_float(rr[0]), __uint_as_float(rr[1])); }
; __device__ __forceinline__ void xattn_mfma_item(const bf16* qx, const bf16* kv, bf16* ox, LAS unsigned char* wl, int item, int lane) {
;     ...
; #pragma unroll
;         for (int d0 = 0; d0 < 8; ++d0) Sx = MFMA32(Kn[d0], Qf[d0], Sx);
;         { LAS unsigned char* dst = wl + (lane >> 4) * PV128 + 16 * (lane & 15);
; #pragma unroll
;           for (int i = 0; i < 8; ++i) *(LAS v4u*)(dst + 4 * i * PV128) = vn[i]; }
;         if (jt < 7) { const char* tb = kvc + (size_t)((jt + 1) * 32) * 2048;
; #pragma unroll
;             for (int d0 = 0; d0 < 8; ++d0) Kn[d0] = *(const s16x8*)(tb + kfo + 32 * d0);
; #pragma unroll
;             for (int i = 0; i < 8; ++i) vn[i] = *(const v4u*)(tb + vlo + (size_t)(4 * i) * 2048); }
;         float P[16]; float tmax = -1e30f;
; #pragma unroll
;         for (int i = 0; i < 16; ++i) { P[i] = Sx[i] * SCX; tmax = fmaxf(tmax, P[i]); }
;         tmax = xh_max(tmax);
;         if (__any(tmax > mrun)) { const float mnew = fmaxf(mrun, tmax), alpha = __builtin_amdgcn_exp2f(mrun - mnew); lsum *= alpha; mrun = mnew;
; #pragma unroll
;             for (int k = 0; k < 4; ++k)
; #pragma unroll
;                 for (int i = 0; i < 16; ++i) O[k][i] *= alpha; }
.LBB0_594:
	s_waitcnt lgkmcnt(0)
	v_mfma_f32_32x32x16_bf16 v[82:97], v[158:161], v[130:133], 0
	s_mov_b32 s2, 0xf149f2ca
	v_mfma_f32_32x32x16_bf16 v[82:97], v[154:157], v[126:129], v[82:97]
	v_mfma_f32_32x32x16_bf16 v[82:97], v[150:153], v[122:125], v[82:97]
	v_mfma_f32_32x32x16_bf16 v[82:97], v[146:149], v[118:121], v[82:97]
	v_mfma_f32_32x32x16_bf16 v[82:97], v[142:145], v[114:117], v[82:97]
	v_mfma_f32_32x32x16_bf16 v[82:97], v[138:141], v[110:113], v[82:97]
	v_mfma_f32_32x32x16_bf16 v[82:97], v[134:137], v[102:105], v[82:97]
	v_mfma_f32_32x32x16_bf16 v[82:97], v[106:109], v[98:101], v[82:97]
	s_barrier
	s_waitcnt vmcnt(0)
	ds_write_b128 v239, v[240:243]
	s_waitcnt lgkmcnt(0)
	s_barrier
	s_nop 11
	v_mul_f32_e32 v82, 0x3e0293ee, v82
	v_mul_f32_e32 v16, 0x3e0293ee, v83
	v_max3_f32 v2, v82, s2, v16
	v_mul_f32_e32 v17, 0x3e0293ee, v84
	v_mul_f32_e32 v15, 0x3e0293ee, v85
	v_max3_f32 v2, v2, v17, v15
	v_mul_f32_e32 v14, 0x3e0293ee, v86
	v_mul_f32_e32 v13, 0x3e0293ee, v87
	v_max3_f32 v2, v2, v14, v13
	v_mul_f32_e32 v12, 0x3e0293ee, v88
	v_mul_f32_e32 v11, 0x3e0293ee, v89
	v_max3_f32 v2, v2, v12, v11
	v_mul_f32_e32 v10, 0x3e0293ee, v90
	v_mul_f32_e32 v9, 0x3e0293ee, v91
	v_max3_f32 v2, v2, v10, v9
	v_mul_f32_e32 v8, 0x3e0293ee, v92
	v_mul_f32_e32 v7, 0x3e0293ee, v93
	v_max3_f32 v2, v2, v8, v7
	v_mul_f32_e32 v6, 0x3e0293ee, v94
	v_mul_f32_e32 v5, 0x3e0293ee, v95
	v_max3_f32 v83, v2, v6, v5
	v_mul_f32_e32 v4, 0x3e0293ee, v96
	v_mul_f32_e32 v2, 0x3e0293ee, v97
	v_max3_f32 v83, v83, v4, v2
	v_mov_b32_e32 v84, v83
	s_nop 1
	v_permlane32_swap_b32_e32 v83, v84
	v_max_f32_e32 v84, v84, v84
	v_max_f32_e32 v83, v83, v83
	v_max_f32_e32 v83, v83, v84
	v_cmp_gt_f32_e32 vcc, v83, v227
	s_cbranch_vccz .LBB0_589
	v_max_f32_e32 v83, v83, v83
	v_max_f32_e32 v84, v227, v227
	v_max_f32_e32 v83, v84, v83
	v_sub_f32_e32 v84, v227, v83
	v_exp_f32_e32 v84, v84
	v_mov_b32_e32 v227, v83
	v_pk_mul_f32 v[80:81], v[80:81], v[84:85] op_sel_hi:[1,0]
	v_pk_mul_f32 v[78:79], v[78:79], v[84:85] op_sel_hi:[1,0]
	v_pk_mul_f32 v[76:77], v[76:77], v[84:85] op_sel_hi:[1,0]
	v_pk_mul_f32 v[74:75], v[74:75], v[84:85] op_sel_hi:[1,0]
	v_pk_mul_f32 v[72:73], v[72:73], v[84:85] op_sel_hi:[1,0]
	v_pk_mul_f32 v[70:71], v[70:71], v[84:85] op_sel_hi:[1,0]
	v_pk_mul_f32 v[68:69], v[68:69], v[84:85] op_sel_hi:[1,0]
	v_pk_mul_f32 v[66:67], v[66:67], v[84:85] op_sel_hi:[1,0]
	v_pk_mul_f32 v[64:65], v[64:65], v[84:85] op_sel_hi:[1,0]
	v_pk_mul_f32 v[62:63], v[62:63], v[84:85] op_sel_hi:[1,0]
	v_pk_mul_f32 v[60:61], v[60:61], v[84:85] op_sel_hi:[1,0]
	v_pk_mul_f32 v[58:59], v[58:59], v[84:85] op_sel_hi:[1,0]
	v_pk_mul_f32 v[56:57], v[56:57], v[84:85] op_sel_hi:[1,0]
	v_pk_mul_f32 v[54:55], v[54:55], v[84:85] op_sel_hi:[1,0]
	v_pk_mul_f32 v[52:53], v[52:53], v[84:85] op_sel_hi:[1,0]
	v_pk_mul_f32 v[50:51], v[50:51], v[84:85] op_sel_hi:[1,0]
	v_pk_mul_f32 v[48:49], v[48:49], v[84:85] op_sel_hi:[1,0]
	v_pk_mul_f32 v[46:47], v[46:47], v[84:85] op_sel_hi:[1,0]
	v_pk_mul_f32 v[44:45], v[44:45], v[84:85] op_sel_hi:[1,0]
	v_pk_mul_f32 v[42:43], v[42:43], v[84:85] op_sel_hi:[1,0]
	v_pk_mul_f32 v[40:41], v[40:41], v[84:85] op_sel_hi:[1,0]
	v_pk_mul_f32 v[38:39], v[38:39], v[84:85] op_sel_hi:[1,0]
	v_pk_mul_f32 v[36:37], v[36:37], v[84:85] op_sel_hi:[1,0]
	v_pk_mul_f32 v[34:35], v[34:35], v[84:85] op_sel_hi:[1,0]
	v_pk_mul_f32 v[32:33], v[32:33], v[84:85] op_sel_hi:[1,0]
	v_pk_mul_f32 v[30:31], v[30:31], v[84:85] op_sel_hi:[1,0]
	v_pk_mul_f32 v[28:29], v[28:29], v[84:85] op_sel_hi:[1,0]
	v_pk_mul_f32 v[26:27], v[26:27], v[84:85] op_sel_hi:[1,0]
	v_pk_mul_f32 v[24:25], v[24:25], v[84:85] op_sel_hi:[1,0]
	v_pk_mul_f32 v[22:23], v[22:23], v[84:85] op_sel_hi:[1,0]
	v_pk_mul_f32 v[20:21], v[20:21], v[84:85] op_sel_hi:[1,0]
	v_pk_mul_f32 v[18:19], v[18:19], v[84:85] op_sel_hi:[1,0]
	v_mul_f32_e32 v226, v226, v84
	s_branch .LBB0_589
